# adds FF1 relu^2 epilogue: the 128 v_max(x,x) canonicalisations before v_max(0,x) dropped (identical for non-signalling inputs), store-data WAR padding re-inserted
# baseline (speedup 1.0000x reference)
; __device__ __forceinline__ u32x4 pack8(f32x4 v0, f32x4 v1) { u32x4 w; w.x = pk2(v0[0], v0[1]); w.y = pk2(v0[2], v0[3]); w.z = pk2(v1[0], v1[1]); w.w = pk2(v1[2], v1[3]); return w; }
;     __device__ __forceinline__ void operator()(const f32x4 (&acc)[2][2][4][2], const Unit& u, int wr, int wc, int fr, int fq) const {
;         const int row0 = u.pm * BM + wr * 64 + fr, col0 = u.pn * BM + wc * 32 + 8 * fq;
; #pragma unroll
;         for (int ai = 0; ai < 2; ++ai)
; #pragma unroll
;             for (int m = 0; m < 4; ++m) { bf16_t* rowp = O + (size_t)(row0 + ai * HALF + m * 16) * DFF + col0;
; #pragma unroll
;                 for (int bj = 0; bj < 2; ++bj) { f32x4 v0 = acc[ai][bj][m][0], v1 = acc[ai][bj][m][1];
; #pragma unroll
;                     for (int j = 0; j < 4; ++j) { const float a0 = fmaxf(v0[j], 0.f), a1 = fmaxf(v1[j], 0.f); v0[j] = a0 * a0; v1[j] = a1 * a1; }
;                     __builtin_nontemporal_store(pack8(v0, v1), (u32x4*)(rowp + bj * HALF)); } }
.LBB0_506:
	v_max_f32_e32 v120, 0, v120
	v_max_f32_e32 v121, 0, v121
	v_pk_mul_f32 v[148:149], v[120:121], v[120:121]
	v_lshl_add_u32 v144, s36, 8, v147
	v_max_f32_e32 v122, 0, v122
	v_ashrrev_i32_e32 v145, 31, v144
	v_max_f32_e32 v124, 0, v124
	v_max_f32_e32 v125, 0, v125
	v_max_f32_e32 v120, 0, v126
	v_max_f32_e32 v121, 0, v127
	v_max_f32_e32 v123, 0, v123
	v_lshlrev_b64 v[140:141], 14, v[144:145]
	v_pk_mul_f32 v[124:125], v[124:125], v[124:125]
	v_pk_mul_f32 v[126:127], v[120:121], v[120:121]
	v_pk_mul_f32 v[150:151], v[122:123], v[122:123]
	v_lshl_add_u64 v[140:141], v[134:135], 0, v[140:141]
	v_cvt_pk_bf16_f32 v120, v124, v125
	v_cvt_pk_bf16_f32 v121, v126, v127
	v_cvt_pk_bf16_f32 v122, v148, v149
	v_cvt_pk_bf16_f32 v123, v150, v151
	v_max_f32_e32 v112, 0, v112
	v_max_f32_e32 v113, 0, v113
	global_store_dwordx4 v[140:141], v[120:123], off nt
	s_nop 1
	v_pk_mul_f32 v[120:121], v[112:113], v[112:113]
	v_max_f32_e32 v114, 0, v114
	v_max_f32_e32 v116, 0, v116
	v_max_f32_e32 v117, 0, v117
	v_max_f32_e32 v112, 0, v118
	v_max_f32_e32 v113, 0, v119
	v_max_f32_e32 v115, 0, v115
	v_pk_mul_f32 v[116:117], v[116:117], v[116:117]
	v_pk_mul_f32 v[118:119], v[112:113], v[112:113]
	v_pk_mul_f32 v[122:123], v[114:115], v[114:115]
	v_cvt_pk_bf16_f32 v112, v116, v117
	v_cvt_pk_bf16_f32 v113, v118, v119
	v_cvt_pk_bf16_f32 v114, v120, v121
	v_cvt_pk_bf16_f32 v115, v122, v123
	v_max_f32_e32 v104, 0, v104
	v_max_f32_e32 v105, 0, v105
	global_store_dwordx4 v[140:141], v[112:115], off offset:256 nt
	s_nop 1
	v_pk_mul_f32 v[114:115], v[104:105], v[104:105]
	v_or_b32_e32 v112, 16, v144
	v_max_f32_e32 v106, 0, v106
	v_ashrrev_i32_e32 v113, 31, v112
	v_max_f32_e32 v108, 0, v108
	v_max_f32_e32 v109, 0, v109
	v_max_f32_e32 v104, 0, v110
	v_max_f32_e32 v105, 0, v111
	v_max_f32_e32 v107, 0, v107
	v_lshlrev_b64 v[112:113], 14, v[112:113]
	v_pk_mul_f32 v[108:109], v[108:109], v[108:109]
	v_pk_mul_f32 v[110:111], v[104:105], v[104:105]
	v_pk_mul_f32 v[116:117], v[106:107], v[106:107]
	v_lshl_add_u64 v[112:113], v[134:135], 0, v[112:113]
	v_cvt_pk_bf16_f32 v104, v108, v109
	v_cvt_pk_bf16_f32 v105, v110, v111
	v_cvt_pk_bf16_f32 v106, v114, v115
	v_cvt_pk_bf16_f32 v107, v116, v117
	v_max_f32_e32 v96, 0, v96
	v_max_f32_e32 v97, 0, v97
	global_store_dwordx4 v[112:113], v[104:107], off nt
	s_nop 1
	v_pk_mul_f32 v[104:105], v[96:97], v[96:97]
	v_max_f32_e32 v98, 0, v98
	v_max_f32_e32 v100, 0, v100
	v_max_f32_e32 v101, 0, v101
	v_max_f32_e32 v96, 0, v102
	v_max_f32_e32 v97, 0, v103
	v_max_f32_e32 v99, 0, v99
	v_pk_mul_f32 v[100:101], v[100:101], v[100:101]
	v_pk_mul_f32 v[102:103], v[96:97], v[96:97]
	v_pk_mul_f32 v[106:107], v[98:99], v[98:99]
	v_cvt_pk_bf16_f32 v96, v100, v101
	v_cvt_pk_bf16_f32 v97, v102, v103
	v_cvt_pk_bf16_f32 v98, v104, v105
	v_cvt_pk_bf16_f32 v99, v106, v107
	v_max_f32_e32 v88, 0, v88
	v_max_f32_e32 v89, 0, v89
	global_store_dwordx4 v[112:113], v[96:99], off offset:256 nt
	s_nop 1
	v_pk_mul_f32 v[98:99], v[88:89], v[88:89]
	v_or_b32_e32 v96, 32, v144
	v_max_f32_e32 v90, 0, v90
	v_ashrrev_i32_e32 v97, 31, v96
	v_max_f32_e32 v92, 0, v92
	v_max_f32_e32 v93, 0, v93
	v_max_f32_e32 v88, 0, v94
	v_max_f32_e32 v89, 0, v95
	v_max_f32_e32 v91, 0, v91
	v_lshlrev_b64 v[96:97], 14, v[96:97]
	v_pk_mul_f32 v[92:93], v[92:93], v[92:93]
	v_pk_mul_f32 v[94:95], v[88:89], v[88:89]
	v_pk_mul_f32 v[100:101], v[90:91], v[90:91]
	v_lshl_add_u64 v[96:97], v[134:135], 0, v[96:97]
	v_cvt_pk_bf16_f32 v88, v92, v93
	v_cvt_pk_bf16_f32 v89, v94, v95
	v_cvt_pk_bf16_f32 v90, v98, v99
	v_cvt_pk_bf16_f32 v91, v100, v101
	v_max_f32_e32 v80, 0, v80
	v_max_f32_e32 v81, 0, v81
	global_store_dwordx4 v[96:97], v[88:91], off nt
	s_nop 1
	v_pk_mul_f32 v[88:89], v[80:81], v[80:81]
	v_max_f32_e32 v82, 0, v82
	v_max_f32_e32 v84, 0, v84
	v_max_f32_e32 v85, 0, v85
	v_max_f32_e32 v80, 0, v86
	v_max_f32_e32 v81, 0, v87
	v_max_f32_e32 v83, 0, v83
	v_pk_mul_f32 v[84:85], v[84:85], v[84:85]
	v_pk_mul_f32 v[86:87], v[80:81], v[80:81]
	v_pk_mul_f32 v[90:91], v[82:83], v[82:83]
	v_cvt_pk_bf16_f32 v80, v84, v85
	v_cvt_pk_bf16_f32 v81, v86, v87
	v_cvt_pk_bf16_f32 v82, v88, v89
	v_cvt_pk_bf16_f32 v83, v90, v91
	v_max_f32_e32 v72, 0, v72
	v_max_f32_e32 v73, 0, v73
	global_store_dwordx4 v[96:97], v[80:83], off offset:256 nt
	s_nop 1
	v_pk_mul_f32 v[82:83], v[72:73], v[72:73]
	v_or_b32_e32 v80, 48, v144
	v_max_f32_e32 v74, 0, v74
	v_ashrrev_i32_e32 v81, 31, v80
	v_max_f32_e32 v76, 0, v76
	v_max_f32_e32 v77, 0, v77
	v_max_f32_e32 v72, 0, v78
	v_max_f32_e32 v73, 0, v79
	v_max_f32_e32 v75, 0, v75
	v_lshlrev_b64 v[80:81], 14, v[80:81]
	v_pk_mul_f32 v[76:77], v[76:77], v[76:77]
	v_pk_mul_f32 v[78:79], v[72:73], v[72:73]
	v_pk_mul_f32 v[84:85], v[74:75], v[74:75]
	v_lshl_add_u64 v[80:81], v[134:135], 0, v[80:81]
	v_cvt_pk_bf16_f32 v72, v76, v77
	v_cvt_pk_bf16_f32 v73, v78, v79
	v_cvt_pk_bf16_f32 v74, v82, v83
	v_cvt_pk_bf16_f32 v75, v84, v85
	v_max_f32_e32 v64, 0, v64
	v_max_f32_e32 v65, 0, v65
	global_store_dwordx4 v[80:81], v[72:75], off nt
	s_nop 1
	v_pk_mul_f32 v[72:73], v[64:65], v[64:65]
	v_max_f32_e32 v66, 0, v66
	v_max_f32_e32 v68, 0, v68
	v_max_f32_e32 v69, 0, v69
	v_max_f32_e32 v64, 0, v70
	v_max_f32_e32 v65, 0, v71
	v_max_f32_e32 v67, 0, v67
	v_pk_mul_f32 v[68:69], v[68:69], v[68:69]
	v_pk_mul_f32 v[70:71], v[64:65], v[64:65]
	v_pk_mul_f32 v[74:75], v[66:67], v[66:67]
	v_cvt_pk_bf16_f32 v64, v68, v69
	v_cvt_pk_bf16_f32 v65, v70, v71
	v_cvt_pk_bf16_f32 v66, v72, v73
	v_cvt_pk_bf16_f32 v67, v74, v75
	v_max_f32_e32 v56, 0, v56
	v_max_f32_e32 v57, 0, v57
; #define PG8_BAR __builtin_amdgcn_s_barrier()
; __device__ __forceinline__ u32x4 pack8(f32x4 v0, f32x4 v1) { u32x4 w; w.x = pk2(v0[0], v0[1]); w.y = pk2(v0[2], v0[3]); w.z = pk2(v1[0], v1[1]); w.w = pk2(v1[2], v1[3]); return w; }
;     ...
;         if (!has_next) break;
; #pragma unroll
;         for (int a = 0; a < 2; ++a)
; #pragma unroll
;             for (int b = 0; b < 2; ++b)
; #pragma unroll
;                 for (int m = 0; m < 4; ++m)
; #pragma unroll
;                     for (int n = 0; n < 2; ++n) acc[a][b][m][n] = (f32x4){0.f, 0.f, 0.f, 0.f};
;         cur = nxt; cA = nA; cB = nB; ++ui;
;         if (wr == 1) PG8_BAR;
;     __device__ __forceinline__ void operator()(const f32x4 (&acc)[2][2][4][2], const Unit& u, int wr, int wc, int fr, int fq) const {
;     ...
;             for (int m = 0; m < 4; ++m) { bf16_t* rowp = O + (size_t)(row0 + ai * HALF + m * 16) * DFF + col0;
; #pragma unroll
;                 for (int bj = 0; bj < 2; ++bj) { f32x4 v0 = acc[ai][bj][m][0], v1 = acc[ai][bj][m][1];
; #pragma unroll
;                     for (int j = 0; j < 4; ++j) { const float a0 = fmaxf(v0[j], 0.f), a1 = fmaxf(v1[j], 0.f); v0[j] = a0 * a0; v1[j] = a1 * a1; }
;                     __builtin_nontemporal_store(pack8(v0, v1), (u32x4*)(rowp + bj * HALF)); } }
	global_store_dwordx4 v[80:81], v[64:67], off offset:256 nt
	s_nop 1
	v_pk_mul_f32 v[66:67], v[56:57], v[56:57]
	s_mov_b64 s[0:1], 0x200000
	v_max_f32_e32 v60, 0, v60
	v_max_f32_e32 v61, 0, v61
	v_max_f32_e32 v58, 0, v58
	v_lshl_add_u64 v[64:65], v[140:141], 0, s[0:1]
	v_pk_mul_f32 v[60:61], v[60:61], v[60:61]
	v_max_f32_e32 v56, 0, v62
	v_max_f32_e32 v57, 0, v63
	v_max_f32_e32 v59, 0, v59
	s_mov_b32 s0, 0x200000
	v_pk_mul_f32 v[62:63], v[56:57], v[56:57]
	v_pk_mul_f32 v[68:69], v[58:59], v[58:59]
	v_cvt_pk_bf16_f32 v56, v60, v61
	v_add_co_u32_e32 v60, vcc, s0, v140
	v_cvt_pk_bf16_f32 v57, v62, v63
	v_cvt_pk_bf16_f32 v58, v66, v67
	v_cvt_pk_bf16_f32 v59, v68, v69
	v_addc_co_u32_e32 v61, vcc, 0, v141, vcc
	v_max_f32_e32 v48, 0, v48
	v_max_f32_e32 v49, 0, v49
	global_store_dwordx4 v[60:61], v[56:59], off nt
	s_nop 1
	v_pk_mul_f32 v[56:57], v[48:49], v[48:49]
	v_max_f32_e32 v50, 0, v50
	v_max_f32_e32 v52, 0, v52
	v_max_f32_e32 v53, 0, v53
	v_max_f32_e32 v48, 0, v54
	v_max_f32_e32 v49, 0, v55
	v_max_f32_e32 v51, 0, v51
	v_pk_mul_f32 v[52:53], v[52:53], v[52:53]
	v_pk_mul_f32 v[54:55], v[48:49], v[48:49]
	v_pk_mul_f32 v[58:59], v[50:51], v[50:51]
	v_cvt_pk_bf16_f32 v48, v52, v53
	v_cvt_pk_bf16_f32 v49, v54, v55
	v_cvt_pk_bf16_f32 v50, v56, v57
	v_cvt_pk_bf16_f32 v51, v58, v59
	v_max_f32_e32 v40, 0, v40
	v_max_f32_e32 v41, 0, v41
	global_store_dwordx4 v[64:65], v[48:51], off offset:256 nt
	s_nop 1
	v_pk_mul_f32 v[50:51], v[40:41], v[40:41]
	s_mov_b64 s[0:1], 0x240000
	v_max_f32_e32 v44, 0, v44
	v_max_f32_e32 v45, 0, v45
	v_max_f32_e32 v42, 0, v42
	v_lshl_add_u64 v[48:49], v[140:141], 0, s[0:1]
	v_pk_mul_f32 v[44:45], v[44:45], v[44:45]
	v_max_f32_e32 v40, 0, v46
	v_max_f32_e32 v41, 0, v47
	v_max_f32_e32 v43, 0, v43
	s_mov_b32 s0, 0x240000
	v_pk_mul_f32 v[46:47], v[40:41], v[40:41]
	v_pk_mul_f32 v[52:53], v[42:43], v[42:43]
	v_cvt_pk_bf16_f32 v40, v44, v45
	v_add_co_u32_e32 v44, vcc, s0, v140
	v_cvt_pk_bf16_f32 v41, v46, v47
	v_cvt_pk_bf16_f32 v42, v50, v51
	v_cvt_pk_bf16_f32 v43, v52, v53
	v_addc_co_u32_e32 v45, vcc, 0, v141, vcc
	v_max_f32_e32 v32, 0, v32
	v_max_f32_e32 v33, 0, v33
	global_store_dwordx4 v[44:45], v[40:43], off nt
	s_nop 1
	v_pk_mul_f32 v[40:41], v[32:33], v[32:33]
	v_max_f32_e32 v34, 0, v34
	v_max_f32_e32 v36, 0, v36
	v_max_f32_e32 v37, 0, v37
	v_max_f32_e32 v32, 0, v38
	v_max_f32_e32 v33, 0, v39
	v_max_f32_e32 v35, 0, v35
	v_pk_mul_f32 v[36:37], v[36:37], v[36:37]
	v_pk_mul_f32 v[38:39], v[32:33], v[32:33]
	v_pk_mul_f32 v[42:43], v[34:35], v[34:35]
	v_cvt_pk_bf16_f32 v32, v36, v37
	v_cvt_pk_bf16_f32 v33, v38, v39
	v_cvt_pk_bf16_f32 v34, v40, v41
	v_cvt_pk_bf16_f32 v35, v42, v43
	v_max_f32_e32 v24, 0, v24
	v_max_f32_e32 v25, 0, v25
	global_store_dwordx4 v[48:49], v[32:35], off offset:256 nt
	s_nop 1
	v_pk_mul_f32 v[34:35], v[24:25], v[24:25]
	s_mov_b64 s[0:1], 0x280000
	v_max_f32_e32 v28, 0, v28
	v_max_f32_e32 v29, 0, v29
	v_max_f32_e32 v26, 0, v26
	v_lshl_add_u64 v[32:33], v[140:141], 0, s[0:1]
	v_pk_mul_f32 v[28:29], v[28:29], v[28:29]
	v_max_f32_e32 v24, 0, v30
	v_max_f32_e32 v25, 0, v31
	v_max_f32_e32 v27, 0, v27
	s_mov_b32 s0, 0x280000
	v_pk_mul_f32 v[30:31], v[24:25], v[24:25]
	v_pk_mul_f32 v[36:37], v[26:27], v[26:27]
	v_cvt_pk_bf16_f32 v24, v28, v29
	v_add_co_u32_e32 v28, vcc, s0, v140
	v_cvt_pk_bf16_f32 v25, v30, v31
	v_cvt_pk_bf16_f32 v26, v34, v35
	v_cvt_pk_bf16_f32 v27, v36, v37
	v_addc_co_u32_e32 v29, vcc, 0, v141, vcc
	v_max_f32_e32 v16, 0, v16
	v_max_f32_e32 v17, 0, v17
	global_store_dwordx4 v[28:29], v[24:27], off nt
	s_nop 1
	v_pk_mul_f32 v[24:25], v[16:17], v[16:17]
	v_max_f32_e32 v18, 0, v18
	v_max_f32_e32 v20, 0, v20
	v_max_f32_e32 v21, 0, v21
	v_max_f32_e32 v16, 0, v22
	v_max_f32_e32 v17, 0, v23
	v_max_f32_e32 v19, 0, v19
	v_pk_mul_f32 v[20:21], v[20:21], v[20:21]
	v_pk_mul_f32 v[22:23], v[16:17], v[16:17]
	v_pk_mul_f32 v[26:27], v[18:19], v[18:19]
	v_cvt_pk_bf16_f32 v16, v20, v21
	v_cvt_pk_bf16_f32 v17, v22, v23
	v_cvt_pk_bf16_f32 v18, v24, v25
	v_cvt_pk_bf16_f32 v19, v26, v27
	v_max_f32_e32 v8, 0, v8
	v_max_f32_e32 v9, 0, v9
	global_store_dwordx4 v[32:33], v[16:19], off offset:256 nt
	s_nop 1
	v_pk_mul_f32 v[18:19], v[8:9], v[8:9]
	s_mov_b64 s[0:1], 0x2c0000
	v_max_f32_e32 v12, 0, v12
	v_max_f32_e32 v13, 0, v13
	v_max_f32_e32 v10, 0, v10
	v_lshl_add_u64 v[16:17], v[140:141], 0, s[0:1]
	v_pk_mul_f32 v[12:13], v[12:13], v[12:13]
	v_max_f32_e32 v8, 0, v14
	v_max_f32_e32 v9, 0, v15
	v_max_f32_e32 v11, 0, v11
	s_mov_b32 s0, 0x2c0000
	v_pk_mul_f32 v[14:15], v[8:9], v[8:9]
	v_pk_mul_f32 v[20:21], v[10:11], v[10:11]
	v_cvt_pk_bf16_f32 v8, v12, v13
	v_add_co_u32_e32 v12, vcc, s0, v140
	v_cvt_pk_bf16_f32 v9, v14, v15
	v_cvt_pk_bf16_f32 v10, v18, v19
	v_cvt_pk_bf16_f32 v11, v20, v21
	v_addc_co_u32_e32 v13, vcc, 0, v141, vcc
	v_max_f32_e32 v0, 0, v0
	v_max_f32_e32 v1, 0, v1
	global_store_dwordx4 v[12:13], v[8:11], off nt
	s_nop 1
	v_pk_mul_f32 v[8:9], v[0:1], v[0:1]
	v_max_f32_e32 v2, 0, v2
	v_max_f32_e32 v4, 0, v4
	v_max_f32_e32 v5, 0, v5
	v_max_f32_e32 v0, 0, v6
	v_max_f32_e32 v1, 0, v7
	v_max_f32_e32 v3, 0, v3
	v_pk_mul_f32 v[4:5], v[4:5], v[4:5]
	v_pk_mul_f32 v[6:7], v[0:1], v[0:1]
	v_pk_mul_f32 v[10:11], v[2:3], v[2:3]
	v_cvt_pk_bf16_f32 v0, v4, v5
	v_cvt_pk_bf16_f32 v1, v6, v7
	v_cvt_pk_bf16_f32 v2, v8, v9
	v_cvt_pk_bf16_f32 v3, v10, v11
	s_cmp_eq_u32 s27, 16
	s_mov_b64 s[0:1], -1
	global_store_dwordx4 v[16:17], v[0:3], off offset:256 nt
	s_cbranch_scc1 .LBB0_501
	s_andn2_b64 vcc, exec, s[12:13]
	s_cbranch_vccnz .LBB0_500
	s_barrier
	s_branch .LBB0_500
